# P1/P4 k-loops: counter / pointer / exit-test SALU hoisted from behind the loop-back barrier into the last MFMA cluster (only the branch follows the barrier)
# speedup vs baseline: 1.0023x; 1.0023x over previous
.Lpeel_mid_p1:
	s_add_i32 s58, 0, 0x18000
	s_add_i32 s59, 0, 0x1c000
	v_add_u32_e32 v140, s58, v186
	v_add_u32_e32 v160, s59, v186
	ds_read_b128 v[128:131], v140
	ds_read_b128 v[132:135], v140 offset:1024
	ds_read_b128 v[136:139], v140 offset:2048
	ds_read_b128 v[140:143], v140 offset:3072
	ds_read_b128 v[144:147], v160
	ds_read_b128 v[148:151], v160 offset:1024
	ds_read_b128 v[176:179], v160 offset:2048
	ds_read_b128 v[180:183], v160 offset:3072
	s_add_u32 s48, s54, 0xa0000
	s_addc_u32 s49, s55, 0
	s_mov_b32 m0, s62
	v_lshl_add_u64 v[232:233], s[48:49], 0, v[152:153]
	ds_read_b128 v[194:197], v190 offset:32768
	ds_read_b128 v[198:201], v190 offset:33792
	ds_read_b128 v[202:205], v190 offset:34816
	ds_read_b128 v[206:209], v190 offset:35840
	ds_read_b128 v[210:213], v190 offset:36864
	ds_read_b128 v[214:217], v190 offset:37888
	ds_read_b128 v[218:221], v190 offset:38912
	ds_read_b128 v[222:225], v190 offset:39936
	global_load_lds_dwordx4 v[232:233], off
	v_lshl_add_u64 v[232:233], s[48:49], 0, v[156:157]
	s_mov_b32 m0, s63
	s_nop 0
	global_load_lds_dwordx4 v[232:233], off
	s_waitcnt vmcnt(8)
	s_waitcnt lgkmcnt(0)
	s_waitcnt lgkmcnt(0)
	s_setprio 1
	s_barrier
	v_mfma_f32_16x16x32_bf16 v[120:123], v[128:131], v[194:197], v[120:123]
	v_mfma_f32_16x16x32_bf16 v[124:127], v[136:139], v[194:197], v[124:127]
	v_mfma_f32_16x16x32_bf16 v[108:111], v[128:131], v[202:205], v[108:111]
	v_mfma_f32_16x16x32_bf16 v[104:107], v[136:139], v[202:205], v[104:107]
	v_mfma_f32_16x16x32_bf16 v[92:95], v[128:131], v[210:213], v[92:95]
	v_mfma_f32_16x16x32_bf16 v[88:91], v[136:139], v[210:213], v[88:91]
	v_mfma_f32_16x16x32_bf16 v[76:79], v[128:131], v[218:221], v[76:79]
	v_mfma_f32_16x16x32_bf16 v[72:75], v[136:139], v[218:221], v[72:75]
	v_mfma_f32_16x16x32_bf16 v[120:123], v[132:135], v[198:201], v[120:123]
	v_mfma_f32_16x16x32_bf16 v[124:127], v[140:143], v[198:201], v[124:127]
	v_mfma_f32_16x16x32_bf16 v[108:111], v[132:135], v[206:209], v[108:111]
	v_mfma_f32_16x16x32_bf16 v[104:107], v[140:143], v[206:209], v[104:107]
	v_mfma_f32_16x16x32_bf16 v[92:95], v[132:135], v[214:217], v[92:95]
	v_mfma_f32_16x16x32_bf16 v[88:91], v[140:143], v[214:217], v[88:91]
	v_mfma_f32_16x16x32_bf16 v[76:79], v[132:135], v[222:225], v[76:79]
	v_mfma_f32_16x16x32_bf16 v[72:75], v[140:143], v[222:225], v[72:75]
	s_setprio 0
	s_setprio 1
	v_mfma_f32_16x16x32_bf16 v[112:115], v[144:147], v[194:197], v[112:115]
	v_mfma_f32_16x16x32_bf16 v[116:119], v[176:179], v[194:197], v[116:119]
	v_mfma_f32_16x16x32_bf16 v[100:103], v[144:147], v[202:205], v[100:103]
	v_mfma_f32_16x16x32_bf16 v[96:99], v[176:179], v[202:205], v[96:99]
	v_mfma_f32_16x16x32_bf16 v[84:87], v[144:147], v[210:213], v[84:87]
	v_mfma_f32_16x16x32_bf16 v[80:83], v[176:179], v[210:213], v[80:83]
	v_mfma_f32_16x16x32_bf16 v[68:71], v[144:147], v[218:221], v[68:71]
	v_mfma_f32_16x16x32_bf16 v[64:67], v[176:179], v[218:221], v[64:67]
	v_mfma_f32_16x16x32_bf16 v[112:115], v[148:151], v[198:201], v[112:115]
	v_mfma_f32_16x16x32_bf16 v[116:119], v[180:183], v[198:201], v[116:119]
	v_mfma_f32_16x16x32_bf16 v[100:103], v[148:151], v[206:209], v[100:103]
	v_mfma_f32_16x16x32_bf16 v[96:99], v[180:183], v[206:209], v[96:99]
	v_mfma_f32_16x16x32_bf16 v[84:87], v[148:151], v[214:217], v[84:87]
	v_mfma_f32_16x16x32_bf16 v[80:83], v[180:183], v[214:217], v[80:83]
	v_mfma_f32_16x16x32_bf16 v[68:71], v[148:151], v[222:225], v[68:71]
	v_mfma_f32_16x16x32_bf16 v[64:67], v[180:183], v[222:225], v[64:67]
	s_barrier
	s_setprio 0
	s_add_i32 s48, s58, s3
	v_lshl_add_u64 v[184:185], v[184:185], 0, s[14:15]
	s_mov_b32 m0, s48
	ds_read_b128 v[194:197], v190 offset:49152
	ds_read_b128 v[198:201], v190 offset:50176
	ds_read_b128 v[202:205], v190 offset:51200
	ds_read_b128 v[206:209], v190 offset:52224
	ds_read_b128 v[210:213], v190 offset:53248
	ds_read_b128 v[214:217], v190 offset:54272
	ds_read_b128 v[218:221], v190 offset:55296
	ds_read_b128 v[222:225], v190 offset:56320
	global_load_lds_dwordx4 v[184:185], off
	s_add_i32 m0, s48, 0x2000
	s_add_u32 s48, s52, 0x80080
	v_lshl_add_u64 v[184:185], v[226:227], 0, s[14:15]
	s_addc_u32 s49, s53, 0
	s_add_i32 s52, s59, s3
	global_load_lds_dwordx4 v[184:185], off
	v_lshl_add_u64 v[184:185], s[48:49], 0, v[154:155]
	s_mov_b32 m0, s52
	s_nop 0
	global_load_lds_dwordx4 v[184:185], off
	v_lshl_add_u64 v[184:185], s[48:49], 0, v[158:159]
	s_add_i32 m0, s52, 0x2000
	s_nop 0
	global_load_lds_dwordx4 v[184:185], off
	v_lshl_add_u64 v[184:185], v[228:229], 0, s[14:15]
	s_mov_b32 m0, s66
	s_nop 0
	global_load_lds_dwordx4 v[184:185], off
	v_lshl_add_u64 v[184:185], v[230:231], 0, s[14:15]
	s_mov_b32 m0, s67
	s_nop 0
	global_load_lds_dwordx4 v[184:185], off
	s_waitcnt vmcnt(8)
	s_waitcnt lgkmcnt(0)
	s_waitcnt lgkmcnt(0)
	s_setprio 1
	s_barrier
	v_mfma_f32_16x16x32_bf16 v[60:63], v[128:131], v[194:197], v[60:63]
	v_mfma_f32_16x16x32_bf16 v[56:59], v[136:139], v[194:197], v[56:59]
	v_mfma_f32_16x16x32_bf16 v[44:47], v[128:131], v[202:205], v[44:47]
	v_mfma_f32_16x16x32_bf16 v[40:43], v[136:139], v[202:205], v[40:43]
	v_mfma_f32_16x16x32_bf16 v[28:31], v[128:131], v[210:213], v[28:31]
	v_mfma_f32_16x16x32_bf16 v[24:27], v[136:139], v[210:213], v[24:27]
	v_mfma_f32_16x16x32_bf16 v[12:15], v[128:131], v[218:221], v[12:15]
	v_mfma_f32_16x16x32_bf16 v[8:11], v[136:139], v[218:221], v[8:11]
	v_mfma_f32_16x16x32_bf16 v[60:63], v[132:135], v[198:201], v[60:63]
	v_mfma_f32_16x16x32_bf16 v[56:59], v[140:143], v[198:201], v[56:59]
	v_mfma_f32_16x16x32_bf16 v[44:47], v[132:135], v[206:209], v[44:47]
	v_mfma_f32_16x16x32_bf16 v[40:43], v[140:143], v[206:209], v[40:43]
	v_mfma_f32_16x16x32_bf16 v[28:31], v[132:135], v[214:217], v[28:31]
	v_mfma_f32_16x16x32_bf16 v[24:27], v[140:143], v[214:217], v[24:27]
	v_mfma_f32_16x16x32_bf16 v[12:15], v[132:135], v[222:225], v[12:15]
	v_mfma_f32_16x16x32_bf16 v[8:11], v[140:143], v[222:225], v[8:11]
	s_setprio 0
	s_setprio 1
	v_mfma_f32_16x16x32_bf16 v[52:55], v[144:147], v[194:197], v[52:55]
	v_mfma_f32_16x16x32_bf16 v[48:51], v[176:179], v[194:197], v[48:51]
	v_mfma_f32_16x16x32_bf16 v[36:39], v[144:147], v[202:205], v[36:39]
	v_mfma_f32_16x16x32_bf16 v[32:35], v[176:179], v[202:205], v[32:35]
	s_add_i32 s57, s57, 2
	v_mfma_f32_16x16x32_bf16 v[20:23], v[144:147], v[210:213], v[20:23]
	s_add_u32 s27, s27, 0x100
	v_mfma_f32_16x16x32_bf16 v[16:19], v[176:179], v[210:213], v[16:19]
	s_addc_u32 s56, s56, 0
	v_mfma_f32_16x16x32_bf16 v[4:7], v[144:147], v[218:221], v[4:7]
	s_cmp_gt_u32 s57, 29
	v_mfma_f32_16x16x32_bf16 v[0:3], v[176:179], v[218:221], v[0:3]
	s_mov_b64 s[48:49], s[50:51]
	v_mfma_f32_16x16x32_bf16 v[52:55], v[148:151], v[198:201], v[52:55]
	v_mfma_f32_16x16x32_bf16 v[48:51], v[180:183], v[198:201], v[48:51]
	v_mfma_f32_16x16x32_bf16 v[36:39], v[148:151], v[206:209], v[36:39]
	v_mfma_f32_16x16x32_bf16 v[32:35], v[180:183], v[206:209], v[32:35]
	v_mfma_f32_16x16x32_bf16 v[20:23], v[148:151], v[214:217], v[20:23]
	v_mfma_f32_16x16x32_bf16 v[16:19], v[180:183], v[214:217], v[16:19]
	v_mfma_f32_16x16x32_bf16 v[4:7], v[148:151], v[222:225], v[4:7]
	v_mfma_f32_16x16x32_bf16 v[0:3], v[180:183], v[222:225], v[0:3]
	s_barrier
	s_setprio 0
	s_cbranch_scc0 .LBB0_146
	s_and_b64 vcc, exec, s[18:19]
	s_cbranch_vccz .LBB0_149
	s_barrier

.Lpeel_mid_p4:
	s_add_i32 s57, 0, 0x18000
	s_add_i32 s58, 0, 0x1c000
	v_add_u32_e32 v140, s57, v184
	v_add_u32_e32 v174, s58, v184
	ds_read_b128 v[128:131], v140
	ds_read_b128 v[132:135], v140 offset:1024
	ds_read_b128 v[136:139], v140 offset:2048
	ds_read_b128 v[140:143], v140 offset:3072
	ds_read_b128 v[162:165], v174
	ds_read_b128 v[166:169], v174 offset:1024
	ds_read_b128 v[170:173], v174 offset:2048
	ds_read_b128 v[174:177], v174 offset:3072
	s_add_u32 s40, s40, 0x80000
	s_addc_u32 s41, s41, 0
	s_mov_b32 m0, s44
	v_lshl_add_u64 v[226:227], s[40:41], 0, v[150:151]
	ds_read_b128 v[178:181], v188 offset:32768
	ds_read_b128 v[192:195], v188 offset:33792
	ds_read_b128 v[196:199], v188 offset:34816
	ds_read_b128 v[200:203], v188 offset:35840
	ds_read_b128 v[204:207], v188 offset:36864
	ds_read_b128 v[208:211], v188 offset:37888
	ds_read_b128 v[212:215], v188 offset:38912
	ds_read_b128 v[216:219], v188 offset:39936
	global_load_lds_dwordx4 v[226:227], off
	v_lshl_add_u64 v[226:227], s[40:41], 0, v[146:147]
	s_mov_b32 m0, s45
	s_nop 0
	global_load_lds_dwordx4 v[226:227], off
	s_waitcnt vmcnt(8)
	s_waitcnt lgkmcnt(0)
	s_waitcnt lgkmcnt(0)
	s_setprio 1
	s_barrier
	v_mfma_f32_16x16x32_bf16 v[124:127], v[128:131], v[178:181], v[124:127]
	v_mfma_f32_16x16x32_bf16 v[120:123], v[136:139], v[178:181], v[120:123]
	v_mfma_f32_16x16x32_bf16 v[108:111], v[128:131], v[196:199], v[108:111]
	v_mfma_f32_16x16x32_bf16 v[104:107], v[136:139], v[196:199], v[104:107]
	v_mfma_f32_16x16x32_bf16 v[92:95], v[128:131], v[204:207], v[92:95]
	v_mfma_f32_16x16x32_bf16 v[88:91], v[136:139], v[204:207], v[88:91]
	v_mfma_f32_16x16x32_bf16 v[76:79], v[128:131], v[212:215], v[76:79]
	v_mfma_f32_16x16x32_bf16 v[72:75], v[136:139], v[212:215], v[72:75]
	v_mfma_f32_16x16x32_bf16 v[124:127], v[132:135], v[192:195], v[124:127]
	v_mfma_f32_16x16x32_bf16 v[120:123], v[140:143], v[192:195], v[120:123]
	v_mfma_f32_16x16x32_bf16 v[108:111], v[132:135], v[200:203], v[108:111]
	v_mfma_f32_16x16x32_bf16 v[104:107], v[140:143], v[200:203], v[104:107]
	v_mfma_f32_16x16x32_bf16 v[92:95], v[132:135], v[208:211], v[92:95]
	v_mfma_f32_16x16x32_bf16 v[88:91], v[140:143], v[208:211], v[88:91]
	v_mfma_f32_16x16x32_bf16 v[76:79], v[132:135], v[216:219], v[76:79]
	v_mfma_f32_16x16x32_bf16 v[72:75], v[140:143], v[216:219], v[72:75]
	s_setprio 0
	s_setprio 1
	v_mfma_f32_16x16x32_bf16 v[116:119], v[162:165], v[178:181], v[116:119]
	v_mfma_f32_16x16x32_bf16 v[112:115], v[170:173], v[178:181], v[112:115]
	v_mfma_f32_16x16x32_bf16 v[100:103], v[162:165], v[196:199], v[100:103]
	v_mfma_f32_16x16x32_bf16 v[96:99], v[170:173], v[196:199], v[96:99]
	v_mfma_f32_16x16x32_bf16 v[84:87], v[162:165], v[204:207], v[84:87]
	v_mfma_f32_16x16x32_bf16 v[80:83], v[170:173], v[204:207], v[80:83]
	v_mfma_f32_16x16x32_bf16 v[68:71], v[162:165], v[212:215], v[68:71]
	v_mfma_f32_16x16x32_bf16 v[64:67], v[170:173], v[212:215], v[64:67]
	v_mfma_f32_16x16x32_bf16 v[116:119], v[166:169], v[192:195], v[116:119]
	v_mfma_f32_16x16x32_bf16 v[112:115], v[174:177], v[192:195], v[112:115]
	v_mfma_f32_16x16x32_bf16 v[100:103], v[166:169], v[200:203], v[100:103]
	v_mfma_f32_16x16x32_bf16 v[96:99], v[174:177], v[200:203], v[96:99]
	v_mfma_f32_16x16x32_bf16 v[84:87], v[166:169], v[208:211], v[84:87]
	v_mfma_f32_16x16x32_bf16 v[80:83], v[174:177], v[208:211], v[80:83]
	v_mfma_f32_16x16x32_bf16 v[68:71], v[166:169], v[216:219], v[68:71]
	v_mfma_f32_16x16x32_bf16 v[64:67], v[174:177], v[216:219], v[64:67]
	s_barrier
	s_setprio 0
	s_add_i32 s40, s57, s35
	v_lshl_add_u64 v[182:183], v[182:183], 0, s[14:15]
	s_mov_b32 m0, s40
	ds_read_b128 v[178:181], v188 offset:49152
	ds_read_b128 v[192:195], v188 offset:50176
	ds_read_b128 v[196:199], v188 offset:51200
	ds_read_b128 v[200:203], v188 offset:52224
	ds_read_b128 v[204:207], v188 offset:53248
	ds_read_b128 v[208:211], v188 offset:54272
	ds_read_b128 v[212:215], v188 offset:55296
	ds_read_b128 v[216:219], v188 offset:56320
	global_load_lds_dwordx4 v[182:183], off
	s_add_i32 m0, s40, 0x2000
	s_add_u32 s38, s38, 0x80080
	v_lshl_add_u64 v[182:183], v[220:221], 0, s[14:15]
	s_addc_u32 s39, s39, 0
	s_add_i32 s40, s58, s35
	global_load_lds_dwordx4 v[182:183], off
	v_lshl_add_u64 v[182:183], s[38:39], 0, v[148:149]
	s_mov_b32 m0, s40
	s_nop 0
	global_load_lds_dwordx4 v[182:183], off
	v_lshl_add_u64 v[182:183], s[38:39], 0, v[144:145]
	s_add_i32 m0, s40, 0x2000
	s_nop 0
	global_load_lds_dwordx4 v[182:183], off
	v_lshl_add_u64 v[182:183], v[222:223], 0, s[14:15]
	s_mov_b32 m0, s49
	s_nop 0
	global_load_lds_dwordx4 v[182:183], off
	v_lshl_add_u64 v[182:183], v[224:225], 0, s[14:15]
	s_mov_b32 m0, s50
	s_nop 0
	global_load_lds_dwordx4 v[182:183], off
	s_waitcnt vmcnt(8)
	s_waitcnt lgkmcnt(0)
	s_waitcnt lgkmcnt(0)
	s_setprio 1
	s_barrier
	v_mfma_f32_16x16x32_bf16 v[60:63], v[128:131], v[178:181], v[60:63]
	v_mfma_f32_16x16x32_bf16 v[56:59], v[136:139], v[178:181], v[56:59]
	v_mfma_f32_16x16x32_bf16 v[44:47], v[128:131], v[196:199], v[44:47]
	v_mfma_f32_16x16x32_bf16 v[40:43], v[136:139], v[196:199], v[40:43]
	v_mfma_f32_16x16x32_bf16 v[28:31], v[128:131], v[204:207], v[28:31]
	v_mfma_f32_16x16x32_bf16 v[24:27], v[136:139], v[204:207], v[24:27]
	v_mfma_f32_16x16x32_bf16 v[12:15], v[128:131], v[212:215], v[12:15]
	v_mfma_f32_16x16x32_bf16 v[8:11], v[136:139], v[212:215], v[8:11]
	v_mfma_f32_16x16x32_bf16 v[60:63], v[132:135], v[192:195], v[60:63]
	v_mfma_f32_16x16x32_bf16 v[56:59], v[140:143], v[192:195], v[56:59]
	v_mfma_f32_16x16x32_bf16 v[44:47], v[132:135], v[200:203], v[44:47]
	v_mfma_f32_16x16x32_bf16 v[40:43], v[140:143], v[200:203], v[40:43]
	v_mfma_f32_16x16x32_bf16 v[28:31], v[132:135], v[208:211], v[28:31]
	v_mfma_f32_16x16x32_bf16 v[24:27], v[140:143], v[208:211], v[24:27]
	v_mfma_f32_16x16x32_bf16 v[12:15], v[132:135], v[216:219], v[12:15]
	v_mfma_f32_16x16x32_bf16 v[8:11], v[140:143], v[216:219], v[8:11]
	s_setprio 0
	s_setprio 1
	v_mfma_f32_16x16x32_bf16 v[52:55], v[162:165], v[178:181], v[52:55]
	v_mfma_f32_16x16x32_bf16 v[48:51], v[170:173], v[178:181], v[48:51]
	v_mfma_f32_16x16x32_bf16 v[36:39], v[162:165], v[196:199], v[36:39]
	v_mfma_f32_16x16x32_bf16 v[32:35], v[170:173], v[196:199], v[32:35]
	s_add_i32 s56, s56, 2
	v_mfma_f32_16x16x32_bf16 v[20:23], v[162:165], v[204:207], v[20:23]
	s_add_u32 s6, s6, 0x100
	v_mfma_f32_16x16x32_bf16 v[16:19], v[170:173], v[204:207], v[16:19]
	s_addc_u32 s7, s7, 0
	v_mfma_f32_16x16x32_bf16 v[4:7], v[162:165], v[212:215], v[4:7]
	s_add_u32 s5, s5, 0x100
	v_mfma_f32_16x16x32_bf16 v[0:3], v[170:173], v[212:215], v[0:3]
	s_addc_u32 s25, s25, 0
	v_mfma_f32_16x16x32_bf16 v[52:55], v[166:169], v[192:195], v[52:55]
	s_cmp_gt_u32 s56, 29
	v_mfma_f32_16x16x32_bf16 v[48:51], v[174:177], v[192:195], v[48:51]
	v_mfma_f32_16x16x32_bf16 v[36:39], v[166:169], v[200:203], v[36:39]
	v_mfma_f32_16x16x32_bf16 v[32:35], v[174:177], v[200:203], v[32:35]
	v_mfma_f32_16x16x32_bf16 v[20:23], v[166:169], v[208:211], v[20:23]
	v_mfma_f32_16x16x32_bf16 v[16:19], v[174:177], v[208:211], v[16:19]
	v_mfma_f32_16x16x32_bf16 v[4:7], v[166:169], v[216:219], v[4:7]
	v_mfma_f32_16x16x32_bf16 v[0:3], v[174:177], v[216:219], v[0:3]
	s_barrier
	s_setprio 0
	s_cbranch_scc0 .LBB0_672
	s_and_b64 vcc, exec, s[18:19]
	s_cbranch_vccz .LBB0_675
	s_barrier
